# combo29: combo23 + permlane16/32-swap reduction steps + prenorm_rows next-row prefetch + pass C g_o loads issued at the unit head (stack of the three individually measured variants)
# baseline (speedup 1.0000x reference)
; __device__ __forceinline__ unsigned pk2(float lo, float hi) { const f32x2 v = {lo, hi}; return __builtin_bit_cast(unsigned, __builtin_convertvector(v, hwbf16x2)); }
; __device__ __forceinline__ void prenorm_rows(const float* __restrict__ xin, bf16_t* __restrict__ an, float* __restrict__ rss, const float* __restrict__ modl, int coff) {
;     ...
;     for (int t = gw; t < T; t += NGW) {
;         const f32x4* xr = (const f32x4*)(xin + (size_t)t * DM) + lane; f32x4 v[4]; float ss = 0.f;
; #pragma unroll
;         for (int j = 0; j < 4; ++j) { v[j] = xr[64 * j]; ss += (v[j][0] * v[j][0] + v[j][1] * v[j][1]) + (v[j][2] * v[j][2] + v[j][3] * v[j][3]); }
;         ss = wave_sum(ss); if (lane == 0) rss[t] = ss;
;         const float* mb = modl + (size_t)(t >> 13) * NMOD;
; #pragma unroll
;         for (int j = 0; j < 4; ++j) { const int col = 256 * j + 4 * lane;
;             const f32x4 sc = *(const f32x4*)(mb + coff + col);
;             const f32x4 h = v[j] * (sc + 1.0f);
;             u32x2 w; w.x = pk2(h[0], h[1]); w.y = pk2(h[2], h[3]); *(u32x2*)(an + (size_t)t * DM + col) = w; }
;     }
.Lpn_loop:
	v_ashrrev_i32_e32 v76, 13, v16
	v_mul_i32_i24_e32 v78, 0x1800, v76
	v_ashrrev_i32_e32 v79, 31, v78
	v_lshl_add_u64 v[78:79], v[78:79], 2, s[76:77]
	v_lshl_add_u64 v[80:81], v[78:79], 0, s[12:13]
	v_lshl_add_u64 v[82:83], v[80:81], 0, v[26:27]
	global_load_dwordx4 v[60:63], v[82:83], off
	v_lshl_add_u64 v[82:83], v[80:81], 0, v[28:29]
	global_load_dwordx4 v[64:67], v[82:83], off
	v_lshl_add_u64 v[82:83], v[80:81], 0, v[18:19]
	global_load_dwordx4 v[68:71], v[82:83], off
	v_mov_b32_e32 v84, v30
	v_mov_b32_e32 v85, v19
	v_lshl_add_u64 v[82:83], v[80:81], 0, v[84:85]
	global_load_dwordx4 v[72:75], v[82:83], off
	v_lshl_add_u64 v[82:83], v[24:25], 0, s[18:19]
	global_load_dwordx4 v[88:91], v[82:83], off
	global_load_dwordx4 v[92:95], v[82:83], off offset:1024
	global_load_dwordx4 v[96:99], v[82:83], off offset:2048
	global_load_dwordx4 v[100:103], v[82:83], off offset:3072
	s_waitcnt vmcnt(11)
	v_mul_f32_e32 v17, v1, v1
	v_mul_f32_e32 v31, v3, v3
	s_waitcnt vmcnt(10)
	v_mul_f32_e32 v38, v5, v5
	v_mul_f32_e32 v39, v7, v7
	s_waitcnt vmcnt(9)
	v_mul_f32_e32 v40, v9, v9
	v_mul_f32_e32 v41, v11, v11
	v_fmac_f32_e32 v17, v0, v0
	v_fmac_f32_e32 v31, v2, v2
	v_fmac_f32_e32 v38, v4, v4
	v_fmac_f32_e32 v39, v6, v6
	s_waitcnt vmcnt(8)
	v_mul_f32_e32 v43, v13, v13
	v_mul_f32_e32 v44, v15, v15
	v_fmac_f32_e32 v40, v8, v8
	v_fmac_f32_e32 v41, v10, v10
	v_add_f32_e32 v17, v17, v31
	v_add_f32_e32 v31, v38, v39
	v_fmac_f32_e32 v43, v12, v12
	v_fmac_f32_e32 v44, v14, v14
	v_add_f32_e32 v38, v40, v41
	v_add_f32_e32 v17, v17, v31
	v_add_f32_e32 v17, v17, v38
	v_add_f32_e32 v31, v43, v44
	v_add_f32_e32 v17, v17, v31
	s_nop 1
	v_add_f32_dpp v17, v17, v17 quad_perm:[1,0,3,2] row_mask:0xf bank_mask:0xf
	s_nop 1
	v_add_f32_dpp v17, v17, v17 quad_perm:[2,3,0,1] row_mask:0xf bank_mask:0xf
	s_nop 1
	v_add_f32_dpp v17, v17, v17 row_half_mirror row_mask:0xf bank_mask:0xf
	s_nop 1
	v_add_f32_dpp v17, v17, v17 row_mirror row_mask:0xf bank_mask:0xf
	s_waitcnt lgkmcnt(0)
	v_mov_b32_e32 v31, v17
	s_nop 1
	v_permlane16_swap_b32_e32 v17, v31
	v_add_f32_e32 v17, v17, v31
	v_mov_b32_e32 v31, v17
	s_nop 1
	v_permlane32_swap_b32_e32 v17, v31
	v_add_f32_e32 v77, v17, v31
	v_lshl_add_u64 v[86:87], s[90:91], 0, v[20:21]
	v_lshl_add_u64 v[56:57], s[90:91], 0, v[22:23]
	v_add_u32_e32 v31, 0x800, v16
	v_cmp_lt_i32_e64 s[2:3], s21, v16
	v_add_co_u32_e64 v16, s[4:5], s20, v56
	v_lshl_add_u64 v[20:21], v[20:21], 0, s[14:15]
	s_nop 0
	v_addc_co_u32_e64 v17, s[4:5], 0, v57, s[4:5]
	v_lshl_add_u64 v[22:23], v[22:23], 0, s[16:17]
	v_lshl_add_u64 v[24:25], v[24:25], 0, s[18:19]
	s_or_b64 s[8:9], s[2:3], s[8:9]
	s_waitcnt vmcnt(7)
	v_pk_add_f32 v[62:63], v[62:63], 1.0 op_sel_hi:[1,0]
	v_pk_add_f32 v[60:61], v[60:61], 1.0 op_sel_hi:[1,0]
	s_waitcnt vmcnt(6)
	v_pk_add_f32 v[66:67], v[66:67], 1.0 op_sel_hi:[1,0]
	v_pk_add_f32 v[64:65], v[64:65], 1.0 op_sel_hi:[1,0]
	s_waitcnt vmcnt(5)
	v_pk_add_f32 v[70:71], v[70:71], 1.0 op_sel_hi:[1,0]
	v_pk_add_f32 v[68:69], v[68:69], 1.0 op_sel_hi:[1,0]
	s_waitcnt vmcnt(4)
	v_pk_add_f32 v[74:75], v[74:75], 1.0 op_sel_hi:[1,0]
	v_pk_add_f32 v[72:73], v[72:73], 1.0 op_sel_hi:[1,0]
	v_pk_mul_f32 v[2:3], v[2:3], v[62:63]
	v_pk_mul_f32 v[0:1], v[0:1], v[60:61]
	v_pk_mul_f32 v[6:7], v[6:7], v[66:67]
	v_pk_mul_f32 v[4:5], v[4:5], v[64:65]
	v_pk_mul_f32 v[10:11], v[10:11], v[70:71]
	v_pk_mul_f32 v[8:9], v[8:9], v[68:69]
	v_pk_mul_f32 v[14:15], v[14:15], v[74:75]
	v_pk_mul_f32 v[12:13], v[12:13], v[72:73]
	v_cvt_pk_bf16_f32 v0, v0, v1
	v_cvt_pk_bf16_f32 v1, v2, v3
	v_cvt_pk_bf16_f32 v2, v4, v5
	v_cvt_pk_bf16_f32 v3, v6, v7
	v_cvt_pk_bf16_f32 v4, v8, v9
	v_cvt_pk_bf16_f32 v5, v10, v11
	v_cvt_pk_bf16_f32 v6, v12, v13
	v_cvt_pk_bf16_f32 v7, v14, v15
	global_store_dwordx2 v[16:17], v[0:1], off
	global_store_dwordx2 v[16:17], v[2:3], off offset:512
	global_store_dwordx2 v[16:17], v[4:5], off offset:1024
	global_store_dwordx2 v[16:17], v[6:7], off offset:1536
	s_mov_b64 s[4:5], exec
	s_and_b64 exec, exec, vcc
	global_store_dword v[86:87], v77, off
	s_mov_b64 exec, s[4:5]
	v_mov_b32_e32 v16, v31
	s_andn2_b64 exec, exec, s[8:9]
	s_cbranch_execz .LBB0_119
	v_readfirstlane_b32 s24, v16
	s_cmp_gt_i32 s24, 0x77ff
	s_cbranch_scc1 .Lpn_last
	v_ashrrev_i32_e32 v76, 13, v16
	v_mul_i32_i24_e32 v78, 0x1800, v76
	v_ashrrev_i32_e32 v79, 31, v78
	v_lshl_add_u64 v[78:79], v[78:79], 2, s[76:77]
	v_lshl_add_u64 v[80:81], v[78:79], 0, s[12:13]
	v_lshl_add_u64 v[82:83], v[80:81], 0, v[26:27]
	global_load_dwordx4 v[60:63], v[82:83], off
	v_lshl_add_u64 v[82:83], v[80:81], 0, v[28:29]
	global_load_dwordx4 v[64:67], v[82:83], off
	v_lshl_add_u64 v[82:83], v[80:81], 0, v[18:19]
	global_load_dwordx4 v[68:71], v[82:83], off
	v_mov_b32_e32 v84, v30
	v_mov_b32_e32 v85, v19
	v_lshl_add_u64 v[82:83], v[80:81], 0, v[84:85]
	global_load_dwordx4 v[72:75], v[82:83], off
	v_lshl_add_u64 v[82:83], v[24:25], 0, s[18:19]
	global_load_dwordx4 v[0:3], v[82:83], off
	global_load_dwordx4 v[4:7], v[82:83], off offset:1024
	global_load_dwordx4 v[8:11], v[82:83], off offset:2048
	global_load_dwordx4 v[12:15], v[82:83], off offset:3072
	s_waitcnt vmcnt(11)
	v_mul_f32_e32 v17, v89, v89
	v_mul_f32_e32 v31, v91, v91
	s_waitcnt vmcnt(10)
	v_mul_f32_e32 v38, v93, v93
	v_mul_f32_e32 v39, v95, v95
	s_waitcnt vmcnt(9)
	v_mul_f32_e32 v40, v97, v97
	v_mul_f32_e32 v41, v99, v99
	v_fmac_f32_e32 v17, v88, v88
	v_fmac_f32_e32 v31, v90, v90
	v_fmac_f32_e32 v38, v92, v92
	v_fmac_f32_e32 v39, v94, v94
	s_waitcnt vmcnt(8)
; __device__ __forceinline__ unsigned pk2(float lo, float hi) { const f32x2 v = {lo, hi}; return __builtin_bit_cast(unsigned, __builtin_convertvector(v, hwbf16x2)); }
; __device__ __forceinline__ void prenorm_rows(const float* __restrict__ xin, bf16_t* __restrict__ an, float* __restrict__ rss, const float* __restrict__ modl, int coff) {
;     ...
;     for (int t = gw; t < T; t += NGW) {
;         const f32x4* xr = (const f32x4*)(xin + (size_t)t * DM) + lane; f32x4 v[4]; float ss = 0.f;
; #pragma unroll
;         for (int j = 0; j < 4; ++j) { v[j] = xr[64 * j]; ss += (v[j][0] * v[j][0] + v[j][1] * v[j][1]) + (v[j][2] * v[j][2] + v[j][3] * v[j][3]); }
;         ss = wave_sum(ss); if (lane == 0) rss[t] = ss;
;         const float* mb = modl + (size_t)(t >> 13) * NMOD;
; #pragma unroll
;         for (int j = 0; j < 4; ++j) { const int col = 256 * j + 4 * lane;
;             const f32x4 sc = *(const f32x4*)(mb + coff + col);
;             const f32x4 h = v[j] * (sc + 1.0f);
;             u32x2 w; w.x = pk2(h[0], h[1]); w.y = pk2(h[2], h[3]); *(u32x2*)(an + (size_t)t * DM + col) = w; }
;     }
	v_mul_f32_e32 v43, v101, v101
	v_mul_f32_e32 v44, v103, v103
	v_fmac_f32_e32 v40, v96, v96
	v_fmac_f32_e32 v41, v98, v98
	v_add_f32_e32 v17, v17, v31
	v_add_f32_e32 v31, v38, v39
	v_fmac_f32_e32 v43, v100, v100
	v_fmac_f32_e32 v44, v102, v102
	v_add_f32_e32 v38, v40, v41
	v_add_f32_e32 v17, v17, v31
	v_add_f32_e32 v17, v17, v38
	v_add_f32_e32 v31, v43, v44
	v_add_f32_e32 v17, v17, v31
	s_nop 1
	v_add_f32_dpp v17, v17, v17 quad_perm:[1,0,3,2] row_mask:0xf bank_mask:0xf
	s_nop 1
	v_add_f32_dpp v17, v17, v17 quad_perm:[2,3,0,1] row_mask:0xf bank_mask:0xf
	s_nop 1
	v_add_f32_dpp v17, v17, v17 row_half_mirror row_mask:0xf bank_mask:0xf
	s_nop 1
	v_add_f32_dpp v17, v17, v17 row_mirror row_mask:0xf bank_mask:0xf
	s_waitcnt lgkmcnt(0)
	v_mov_b32_e32 v31, v17
	s_nop 1
	v_permlane16_swap_b32_e32 v17, v31
	v_add_f32_e32 v17, v17, v31
	v_mov_b32_e32 v31, v17
	s_nop 1
	v_permlane32_swap_b32_e32 v17, v31
	v_add_f32_e32 v77, v17, v31
	v_lshl_add_u64 v[86:87], s[90:91], 0, v[20:21]
	v_lshl_add_u64 v[56:57], s[90:91], 0, v[22:23]
	v_add_u32_e32 v31, 0x800, v16
	v_cmp_lt_i32_e64 s[2:3], s21, v16
	v_add_co_u32_e64 v16, s[4:5], s20, v56
	v_lshl_add_u64 v[20:21], v[20:21], 0, s[14:15]
	s_nop 0
	v_addc_co_u32_e64 v17, s[4:5], 0, v57, s[4:5]
	v_lshl_add_u64 v[22:23], v[22:23], 0, s[16:17]
	v_lshl_add_u64 v[24:25], v[24:25], 0, s[18:19]
	s_or_b64 s[8:9], s[2:3], s[8:9]
	s_waitcnt vmcnt(7)
	v_pk_add_f32 v[62:63], v[62:63], 1.0 op_sel_hi:[1,0]
	v_pk_add_f32 v[60:61], v[60:61], 1.0 op_sel_hi:[1,0]
	s_waitcnt vmcnt(6)
	v_pk_add_f32 v[66:67], v[66:67], 1.0 op_sel_hi:[1,0]
	v_pk_add_f32 v[64:65], v[64:65], 1.0 op_sel_hi:[1,0]
	s_waitcnt vmcnt(5)
	v_pk_add_f32 v[70:71], v[70:71], 1.0 op_sel_hi:[1,0]
	v_pk_add_f32 v[68:69], v[68:69], 1.0 op_sel_hi:[1,0]
	s_waitcnt vmcnt(4)
	v_pk_add_f32 v[74:75], v[74:75], 1.0 op_sel_hi:[1,0]
	v_pk_add_f32 v[72:73], v[72:73], 1.0 op_sel_hi:[1,0]
	v_pk_mul_f32 v[90:91], v[90:91], v[62:63]
	v_pk_mul_f32 v[88:89], v[88:89], v[60:61]
	v_pk_mul_f32 v[94:95], v[94:95], v[66:67]
	v_pk_mul_f32 v[92:93], v[92:93], v[64:65]
	v_pk_mul_f32 v[98:99], v[98:99], v[70:71]
	v_pk_mul_f32 v[96:97], v[96:97], v[68:69]
	v_pk_mul_f32 v[102:103], v[102:103], v[74:75]
	v_pk_mul_f32 v[100:101], v[100:101], v[72:73]
	v_cvt_pk_bf16_f32 v88, v88, v89
	v_cvt_pk_bf16_f32 v89, v90, v91
	v_cvt_pk_bf16_f32 v90, v92, v93
	v_cvt_pk_bf16_f32 v91, v94, v95
	v_cvt_pk_bf16_f32 v92, v96, v97
	v_cvt_pk_bf16_f32 v93, v98, v99
	v_cvt_pk_bf16_f32 v94, v100, v101
	v_cvt_pk_bf16_f32 v95, v102, v103
	global_store_dwordx2 v[16:17], v[88:89], off
	global_store_dwordx2 v[16:17], v[90:91], off offset:512
	global_store_dwordx2 v[16:17], v[92:93], off offset:1024
	global_store_dwordx2 v[16:17], v[94:95], off offset:1536
	s_mov_b64 s[4:5], exec
	s_and_b64 exec, exec, vcc
	global_store_dword v[86:87], v77, off
	s_mov_b64 exec, s[4:5]
	v_mov_b32_e32 v16, v31
	s_andn2_b64 exec, exec, s[8:9]
	s_cbranch_execz .LBB0_119
	s_branch .Lpn_loop
.Lpn_last:
	v_ashrrev_i32_e32 v76, 13, v16
	v_mul_i32_i24_e32 v78, 0x1800, v76
	v_ashrrev_i32_e32 v79, 31, v78
	v_lshl_add_u64 v[78:79], v[78:79], 2, s[76:77]
	v_lshl_add_u64 v[80:81], v[78:79], 0, s[12:13]
	v_lshl_add_u64 v[82:83], v[80:81], 0, v[26:27]
	global_load_dwordx4 v[60:63], v[82:83], off
	v_lshl_add_u64 v[82:83], v[80:81], 0, v[28:29]
	global_load_dwordx4 v[64:67], v[82:83], off
	v_lshl_add_u64 v[82:83], v[80:81], 0, v[18:19]
	global_load_dwordx4 v[68:71], v[82:83], off
	v_mov_b32_e32 v84, v30
	v_mov_b32_e32 v85, v19
	v_lshl_add_u64 v[82:83], v[80:81], 0, v[84:85]
	global_load_dwordx4 v[72:75], v[82:83], off
	s_waitcnt vmcnt(7)
	v_mul_f32_e32 v17, v89, v89
	v_mul_f32_e32 v31, v91, v91
	s_waitcnt vmcnt(6)
	v_mul_f32_e32 v38, v93, v93
	v_mul_f32_e32 v39, v95, v95
	s_waitcnt vmcnt(5)
	v_mul_f32_e32 v40, v97, v97
	v_mul_f32_e32 v41, v99, v99
	v_fmac_f32_e32 v17, v88, v88
	v_fmac_f32_e32 v31, v90, v90
	v_fmac_f32_e32 v38, v92, v92
	v_fmac_f32_e32 v39, v94, v94
	s_waitcnt vmcnt(4)
	v_mul_f32_e32 v43, v101, v101
	v_mul_f32_e32 v44, v103, v103
	v_fmac_f32_e32 v40, v96, v96
	v_fmac_f32_e32 v41, v98, v98
	v_add_f32_e32 v17, v17, v31
	v_add_f32_e32 v31, v38, v39
	v_fmac_f32_e32 v43, v100, v100
	v_fmac_f32_e32 v44, v102, v102
	v_add_f32_e32 v38, v40, v41
	v_add_f32_e32 v17, v17, v31
	v_add_f32_e32 v17, v17, v38
	v_add_f32_e32 v31, v43, v44
	v_add_f32_e32 v17, v17, v31
	s_nop 1
	v_add_f32_dpp v17, v17, v17 quad_perm:[1,0,3,2] row_mask:0xf bank_mask:0xf
	s_nop 1
	v_add_f32_dpp v17, v17, v17 quad_perm:[2,3,0,1] row_mask:0xf bank_mask:0xf
	s_nop 1
	v_add_f32_dpp v17, v17, v17 row_half_mirror row_mask:0xf bank_mask:0xf
	s_nop 1
	v_add_f32_dpp v17, v17, v17 row_mirror row_mask:0xf bank_mask:0xf
	s_waitcnt lgkmcnt(0)
	v_mov_b32_e32 v31, v17
	s_nop 1
	v_permlane16_swap_b32_e32 v17, v31
	v_add_f32_e32 v17, v17, v31
	v_mov_b32_e32 v31, v17
	s_nop 1
	v_permlane32_swap_b32_e32 v17, v31
	v_add_f32_e32 v77, v17, v31
	v_lshl_add_u64 v[86:87], s[90:91], 0, v[20:21]
	v_lshl_add_u64 v[56:57], s[90:91], 0, v[22:23]
	v_add_u32_e32 v31, 0x800, v16
	v_cmp_lt_i32_e64 s[2:3], s21, v16
	v_add_co_u32_e64 v16, s[4:5], s20, v56
	v_lshl_add_u64 v[20:21], v[20:21], 0, s[14:15]
	s_nop 0
	v_addc_co_u32_e64 v17, s[4:5], 0, v57, s[4:5]
	v_lshl_add_u64 v[22:23], v[22:23], 0, s[16:17]
	v_lshl_add_u64 v[24:25], v[24:25], 0, s[18:19]
	s_or_b64 s[8:9], s[2:3], s[8:9]
	s_waitcnt vmcnt(3)
	v_pk_add_f32 v[62:63], v[62:63], 1.0 op_sel_hi:[1,0]
	v_pk_add_f32 v[60:61], v[60:61], 1.0 op_sel_hi:[1,0]
	s_waitcnt vmcnt(2)
	v_pk_add_f32 v[66:67], v[66:67], 1.0 op_sel_hi:[1,0]
	v_pk_add_f32 v[64:65], v[64:65], 1.0 op_sel_hi:[1,0]
	s_waitcnt vmcnt(1)
	v_pk_add_f32 v[70:71], v[70:71], 1.0 op_sel_hi:[1,0]
	v_pk_add_f32 v[68:69], v[68:69], 1.0 op_sel_hi:[1,0]
	s_waitcnt vmcnt(0)
	v_pk_add_f32 v[74:75], v[74:75], 1.0 op_sel_hi:[1,0]
	v_pk_add_f32 v[72:73], v[72:73], 1.0 op_sel_hi:[1,0]
	v_pk_mul_f32 v[90:91], v[90:91], v[62:63]
	v_pk_mul_f32 v[88:89], v[88:89], v[60:61]
	v_pk_mul_f32 v[94:95], v[94:95], v[66:67]
	v_pk_mul_f32 v[92:93], v[92:93], v[64:65]
	v_pk_mul_f32 v[98:99], v[98:99], v[70:71]
	v_pk_mul_f32 v[96:97], v[96:97], v[68:69]
	v_pk_mul_f32 v[102:103], v[102:103], v[74:75]
	v_pk_mul_f32 v[100:101], v[100:101], v[72:73]
	v_cvt_pk_bf16_f32 v88, v88, v89
	v_cvt_pk_bf16_f32 v89, v90, v91
	v_cvt_pk_bf16_f32 v90, v92, v93
	v_cvt_pk_bf16_f32 v91, v94, v95
	v_cvt_pk_bf16_f32 v92, v96, v97
	v_cvt_pk_bf16_f32 v93, v98, v99
	v_cvt_pk_bf16_f32 v94, v100, v101
	v_cvt_pk_bf16_f32 v95, v102, v103
	global_store_dwordx2 v[16:17], v[88:89], off
	global_store_dwordx2 v[16:17], v[90:91], off offset:512
	global_store_dwordx2 v[16:17], v[92:93], off offset:1024
	global_store_dwordx2 v[16:17], v[94:95], off offset:1536
	s_mov_b64 s[4:5], exec
	s_and_b64 exec, exec, vcc
	global_store_dword v[86:87], v77, off
	s_mov_b64 exec, s[4:5]
	v_mov_b32_e32 v16, v31
	s_andn2_b64 exec, exec, s[8:9]
	s_cbranch_execz .LBB0_119
	s_branch .LBB0_119

; #define LAS __attribute__((address_space(3)))
; __device__ __forceinline__ int crow(int r, int hi) { return (r & 3) + 8 * (r >> 2) + 4 * hi; }
; __device__ __forceinline__ float bf2f(unsigned short v) { return __uint_as_float((unsigned)v << 16); }
; __device__ __forceinline__ unsigned f2bf(float f) { return pk2(f, 0.f) & 0xffffu; }
; __device__ __forceinline__ int crow(int r, int hi) { return (r & 3) + 8 * (r >> 2) + 4 * hi; }
; __device__ __forceinline__ void gla_pass_c(LAS unsigned char* ldsl, const bf16_t* __restrict__ proj, const float* __restrict__ Btab, const float* __restrict__ Gst, const float* __restrict__ gout, bf16_t* __restrict__ mixed) {
;     ...
;         { const bf16_t* gp = proj + (row0 + 32 * tb + crw) * NIN + 1024 + h * 128 + ccl * 8; u32x4 sv[8];
; #pragma unroll
;           for (int i = 0; i < 8; ++i) sv[i] = *(const u32x4*)(gp + (size_t)(4 * i) * NIN);
; #pragma unroll
;           for (int i = 0; i < 8; ++i) *(LAS u32x4*)(Lw + (4 * i + crw) * 256 + ccl * 16) = sv[i]; }
;     ...
;         for (int i = 0; i < 16; ++i) { const int tr = crow(i, hh);
;             const float tot = half_sum32((o[0][i] * o[0][i] + o[1][i] * o[1][i]) + (o[2][i] * o[2][i] + o[3][i] * o[3][i]));
;             const float rr = __builtin_amdgcn_rsqf(tot * (1.0f / 128.0f) + EPS);
; #pragma unroll
;             for (int dvb = 0; dvb < 4; ++dvb) { const float g = bf2f(Lh[tr * 128 + 32 * dvb + r]);
;                 const float val = o[dvb][i] * rr * gn[dvb] * (g * __builtin_amdgcn_rcpf(1.0f + __expf(-g)));
;                 Lh[(32 + tr) * 128 + 32 * dvb + r] = (bf16_t)f2bf(val); } }
.LBB0_873:
	v_or3_b32 v122, s2, v110, v122
	v_lshlrev_b64 v[64:65], 12, v[122:123]
	v_lshl_add_u64 v[64:65], s[60:61], 0, v[64:65]
	v_lshlrev_b32_e32 v160, 1, v124
	v_lshl_add_u64 v[64:65], v[64:65], 0, v[160:161]
	v_mov_b32_e32 v121, v161
	v_lshl_add_u64 v[92:93], v[64:65], 0, v[120:121]
	v_add_co_u32_e32 v68, vcc, 0x4000, v92
	s_nop 0
	v_addc_co_u32_e32 v69, vcc, 0, v93, vcc
	v_add_co_u32_e32 v72, vcc, 0x8000, v92
	s_nop 0
	v_addc_co_u32_e32 v73, vcc, 0, v93, vcc
	v_add_co_u32_e32 v76, vcc, 0xc000, v92
	s_nop 0
	v_addc_co_u32_e32 v77, vcc, 0, v93, vcc
	v_add_co_u32_e32 v80, vcc, s51, v92
	s_mov_b32 s33, 0x18000
	s_nop 0
	v_addc_co_u32_e32 v81, vcc, 0, v93, vcc
	v_add_co_u32_e32 v84, vcc, s52, v92
	s_nop 0
	v_addc_co_u32_e32 v85, vcc, 0, v93, vcc
	v_add_co_u32_e32 v88, vcc, s33, v92
	s_nop 0
	v_addc_co_u32_e32 v89, vcc, 0, v93, vcc
	s_mov_b32 s2, 0x1c000
	v_add_co_u32_e32 v92, vcc, s2, v92
	s_nop 0
	v_addc_co_u32_e32 v93, vcc, 0, v93, vcc
	s_movk_i32 s2, 0x2000
	s_mov_b32 s42, 0x8000
	s_waitcnt vmcnt(0)
	ds_write_b128 v140, v[206:209]
	ds_write_b128 v140, v[210:213] offset:1024
	ds_write_b128 v140, v[214:217] offset:2048
	ds_write_b128 v140, v[218:221] offset:3072
	ds_write_b128 v140, v[222:225] offset:4096
	ds_write_b128 v140, v[226:229] offset:5120
	ds_write_b128 v140, v[230:233] offset:6144
	ds_write_b128 v140, v[234:237] offset:7168
	v_mul_f32_e32 v64, v16, v16
	v_mul_f32_e32 v65, v32, v32
	v_fmac_f32_e32 v64, v0, v0
	v_fmac_f32_e32 v65, v48, v48
	v_add_f32_e32 v64, v64, v65
	ds_read_u16 v144, v138
	ds_read_u16 v145, v138 offset:64
	ds_read_u16 v146, v138 offset:128
	ds_read_u16 v147, v138 offset:192
	s_nop 1
	v_add_f32_dpp v64, v64, v64 quad_perm:[1,0,3,2] row_mask:0xf bank_mask:0xf
	s_nop 1
	v_add_f32_dpp v64, v64, v64 quad_perm:[2,3,0,1] row_mask:0xf bank_mask:0xf
	s_nop 1
	v_add_f32_dpp v64, v64, v64 row_half_mirror row_mask:0xf bank_mask:0xf
	s_nop 1
	v_add_f32_dpp v64, v64, v64 row_mirror row_mask:0xf bank_mask:0xf
	s_waitcnt lgkmcnt(0)
	v_mov_b32_e32 v65, v64
	s_nop 1
	v_permlane16_swap_b32_e32 v64, v65
	v_add_f32_e32 v64, v64, v65
	v_fmamk_f32 v64, v64, 0x3c000000, v199
	v_rsq_f32_e32 v64, v64
	v_lshlrev_b32_e32 v65, 16, v144
	v_mul_f32_e32 v66, 0xbfb8aa3b, v65
	v_exp_f32_e32 v66, v66
	v_mul_f32_e32 v0, v0, v64
	v_mul_f32_e32 v0, v113, v0
	v_mul_f32_e32 v16, v16, v64
	v_add_f32_e32 v66, 1.0, v66
	v_rcp_f32_e32 v66, v66
	v_mul_f32_e32 v16, v130, v16
	v_mul_f32_e32 v65, v66, v65
	v_mul_f32_e32 v0, v0, v65
	v_cvt_pk_bf16_f32 v0, v0, s0
	ds_write_b16 v138, v0 offset:8192
	v_lshlrev_b32_e32 v0, 16, v145
	v_mul_f32_e32 v65, 0xbfb8aa3b, v0
	v_exp_f32_e32 v65, v65
	s_nop 0
	v_add_f32_e32 v65, 1.0, v65
	v_rcp_f32_e32 v65, v65
	s_nop 0
	v_mul_f32_e32 v0, v65, v0
	v_mul_f32_e32 v0, v16, v0
	v_cvt_pk_bf16_f32 v0, v0, s0
	ds_write_b16 v138, v0 offset:8256
	v_mul_f32_e32 v16, v48, v64
	v_mul_f32_e32 v16, v131, v16
	v_lshlrev_b32_e32 v0, 16, v146
	v_mul_f32_e32 v48, 0xbfb8aa3b, v0
	v_exp_f32_e32 v48, v48
	s_nop 0
	v_add_f32_e32 v48, 1.0, v48
	v_rcp_f32_e32 v48, v48
	s_nop 0
	v_mul_f32_e32 v0, v48, v0
	v_mul_f32_e32 v0, v16, v0
	v_cvt_pk_bf16_f32 v0, v0, s0
	ds_write_b16 v138, v0 offset:8320
	v_mul_f32_e32 v16, v32, v64
	v_mul_f32_e32 v16, v132, v16
	v_lshlrev_b32_e32 v0, 16, v147
	v_mul_f32_e32 v32, 0xbfb8aa3b, v0
	v_exp_f32_e32 v32, v32
	s_nop 0
	v_add_f32_e32 v32, 1.0, v32
	v_rcp_f32_e32 v32, v32
	s_nop 0
	v_mul_f32_e32 v0, v32, v0
	v_mul_f32_e32 v0, v16, v0
	v_cvt_pk_bf16_f32 v0, v0, s0
	ds_write_b16 v138, v0 offset:8384
	v_mul_f32_e32 v0, v17, v17
	v_mul_f32_e32 v16, v33, v33
	v_fmac_f32_e32 v0, v1, v1
	v_fmac_f32_e32 v16, v49, v49
	v_add_f32_e32 v0, v0, v16
	ds_read_u16 v144, v138 offset:256
	ds_read_u16 v145, v138 offset:320
	ds_read_u16 v146, v138 offset:384
	ds_read_u16 v147, v138 offset:448
	s_nop 1
	v_add_f32_dpp v0, v0, v0 quad_perm:[1,0,3,2] row_mask:0xf bank_mask:0xf
	s_nop 1
	v_add_f32_dpp v0, v0, v0 quad_perm:[2,3,0,1] row_mask:0xf bank_mask:0xf
	s_nop 1
	v_add_f32_dpp v0, v0, v0 row_half_mirror row_mask:0xf bank_mask:0xf
	s_nop 1
	v_add_f32_dpp v0, v0, v0 row_mirror row_mask:0xf bank_mask:0xf
	s_waitcnt lgkmcnt(0)
	v_mov_b32_e32 v16, v0
	s_nop 1
	v_permlane16_swap_b32_e32 v0, v16
	v_add_f32_e32 v0, v0, v16
	v_fmamk_f32 v0, v0, 0x3c000000, v199
	v_rsq_f32_e32 v0, v0
	v_lshlrev_b32_e32 v16, 16, v144
	v_mul_f32_e32 v32, 0xbfb8aa3b, v16
	v_exp_f32_e32 v32, v32
	v_mul_f32_e32 v1, v1, v0
	v_mul_f32_e32 v1, v113, v1
	v_add_f32_e32 v32, 1.0, v32
	v_rcp_f32_e32 v32, v32
	s_nop 0
	v_mul_f32_e32 v16, v32, v16
	v_mul_f32_e32 v1, v1, v16
	v_cvt_pk_bf16_f32 v1, v1, s0
	ds_write_b16 v138, v1 offset:8448
	v_mul_f32_e32 v16, v17, v0
	v_mul_f32_e32 v16, v130, v16
	v_lshlrev_b32_e32 v1, 16, v145
	v_mul_f32_e32 v17, 0xbfb8aa3b, v1
	v_exp_f32_e32 v17, v17
	s_nop 0
	v_add_f32_e32 v17, 1.0, v17
	v_rcp_f32_e32 v17, v17
	s_nop 0
	v_mul_f32_e32 v1, v17, v1
	v_mul_f32_e32 v1, v16, v1
	v_cvt_pk_bf16_f32 v1, v1, s0
	ds_write_b16 v138, v1 offset:8512
	v_mul_f32_e32 v16, v49, v0
	v_mul_f32_e32 v16, v131, v16
	v_mul_f32_e32 v0, v33, v0
	v_mul_f32_e32 v0, v132, v0
	v_lshlrev_b32_e32 v1, 16, v146
	v_mul_f32_e32 v17, 0xbfb8aa3b, v1
	v_exp_f32_e32 v17, v17
	s_nop 0
	v_add_f32_e32 v17, 1.0, v17
	v_rcp_f32_e32 v17, v17
	s_nop 0
	v_mul_f32_e32 v1, v17, v1
	v_mul_f32_e32 v1, v16, v1
	v_cvt_pk_bf16_f32 v1, v1, s0
	ds_write_b16 v138, v1 offset:8576
	v_lshlrev_b32_e32 v1, 16, v147
	v_mul_f32_e32 v16, 0xbfb8aa3b, v1
	v_exp_f32_e32 v16, v16
	s_nop 0
	v_add_f32_e32 v16, 1.0, v16
	v_rcp_f32_e32 v16, v16
	s_nop 0
	v_mul_f32_e32 v1, v16, v1
	v_mul_f32_e32 v0, v0, v1
	v_cvt_pk_bf16_f32 v0, v0, s0
	ds_write_b16 v138, v0 offset:8640
	v_mul_f32_e32 v0, v18, v18
	v_mul_f32_e32 v1, v34, v34
	v_fmac_f32_e32 v0, v2, v2
	v_fmac_f32_e32 v1, v50, v50
	v_add_f32_e32 v0, v0, v1
	ds_read_u16 v144, v138 offset:512
	ds_read_u16 v145, v138 offset:576
	ds_read_u16 v146, v138 offset:640
	ds_read_u16 v147, v138 offset:704
	s_nop 1
	v_add_f32_dpp v0, v0, v0 quad_perm:[1,0,3,2] row_mask:0xf bank_mask:0xf
	s_nop 1
	v_add_f32_dpp v0, v0, v0 quad_perm:[2,3,0,1] row_mask:0xf bank_mask:0xf
	s_nop 1
	v_add_f32_dpp v0, v0, v0 row_half_mirror row_mask:0xf bank_mask:0xf
	s_nop 1
	v_add_f32_dpp v0, v0, v0 row_mirror row_mask:0xf bank_mask:0xf
	s_waitcnt lgkmcnt(0)
; __device__ __forceinline__ int crow(int r, int hi) { return (r & 3) + 8 * (r >> 2) + 4 * hi; }
; __device__ __forceinline__ float bf2f(unsigned short v) { return __uint_as_float((unsigned)v << 16); }
; __device__ __forceinline__ unsigned f2bf(float f) { return pk2(f, 0.f) & 0xffffu; }
; __device__ __forceinline__ int crow(int r, int hi) { return (r & 3) + 8 * (r >> 2) + 4 * hi; }
; __device__ __forceinline__ void gla_pass_c(LAS unsigned char* ldsl, const bf16_t* __restrict__ proj, const float* __restrict__ Btab, const float* __restrict__ Gst, const float* __restrict__ gout, bf16_t* __restrict__ mixed) {
;     ...
;         for (int i = 0; i < 16; ++i) { const int tr = crow(i, hh);
;             const float tot = half_sum32((o[0][i] * o[0][i] + o[1][i] * o[1][i]) + (o[2][i] * o[2][i] + o[3][i] * o[3][i]));
;             const float rr = __builtin_amdgcn_rsqf(tot * (1.0f / 128.0f) + EPS);
; #pragma unroll
;             for (int dvb = 0; dvb < 4; ++dvb) { const float g = bf2f(Lh[tr * 128 + 32 * dvb + r]);
;                 const float val = o[dvb][i] * rr * gn[dvb] * (g * __builtin_amdgcn_rcpf(1.0f + __expf(-g)));
;                 Lh[(32 + tr) * 128 + 32 * dvb + r] = (bf16_t)f2bf(val); } }
	v_mov_b32_e32 v1, v0
	s_nop 1
	v_permlane16_swap_b32_e32 v0, v1
	v_add_f32_e32 v0, v0, v1
	v_fmamk_f32 v0, v0, 0x3c000000, v199
	v_rsq_f32_e32 v0, v0
	v_lshlrev_b32_e32 v1, 16, v144
	v_mul_f32_e32 v16, 0xbfb8aa3b, v1
	v_exp_f32_e32 v16, v16
	v_mul_f32_e32 v2, v2, v0
	v_mul_f32_e32 v2, v113, v2
	v_add_f32_e32 v16, 1.0, v16
	v_rcp_f32_e32 v16, v16
	s_nop 0
	v_mul_f32_e32 v1, v16, v1
	v_mul_f32_e32 v1, v2, v1
	v_cvt_pk_bf16_f32 v1, v1, s0
	ds_write_b16 v138, v1 offset:8704
	v_mul_f32_e32 v2, v18, v0
	v_mul_f32_e32 v2, v130, v2
	v_lshlrev_b32_e32 v1, 16, v145
	v_mul_f32_e32 v16, 0xbfb8aa3b, v1
	v_exp_f32_e32 v16, v16
	s_nop 0
	v_add_f32_e32 v16, 1.0, v16
	v_rcp_f32_e32 v16, v16
	s_nop 0
	v_mul_f32_e32 v1, v16, v1
	v_mul_f32_e32 v1, v2, v1
	v_cvt_pk_bf16_f32 v1, v1, s0
	ds_write_b16 v138, v1 offset:8768
	v_mul_f32_e32 v2, v50, v0
	v_mul_f32_e32 v2, v131, v2
	v_mul_f32_e32 v0, v34, v0
	v_mul_f32_e32 v0, v132, v0
	v_lshlrev_b32_e32 v1, 16, v146
	v_mul_f32_e32 v16, 0xbfb8aa3b, v1
	v_exp_f32_e32 v16, v16
	s_nop 0
	v_add_f32_e32 v16, 1.0, v16
	v_rcp_f32_e32 v16, v16
	s_nop 0
	v_mul_f32_e32 v1, v16, v1
	v_mul_f32_e32 v1, v2, v1
	v_cvt_pk_bf16_f32 v1, v1, s0
	ds_write_b16 v138, v1 offset:8832
	v_lshlrev_b32_e32 v1, 16, v147
	v_mul_f32_e32 v2, 0xbfb8aa3b, v1
	v_exp_f32_e32 v2, v2
	s_nop 0
	v_add_f32_e32 v2, 1.0, v2
	v_rcp_f32_e32 v2, v2
	s_nop 0
	v_mul_f32_e32 v1, v2, v1
	v_mul_f32_e32 v0, v0, v1
	v_cvt_pk_bf16_f32 v0, v0, s0
	ds_write_b16 v138, v0 offset:8896
	v_mul_f32_e32 v0, v19, v19
	v_mul_f32_e32 v1, v35, v35
	v_fmac_f32_e32 v0, v3, v3
	v_fmac_f32_e32 v1, v51, v51
	v_add_f32_e32 v0, v0, v1
	ds_read_u16 v144, v138 offset:768
	ds_read_u16 v145, v138 offset:832
	ds_read_u16 v146, v138 offset:896
	ds_read_u16 v147, v138 offset:960
	s_nop 1
	v_add_f32_dpp v0, v0, v0 quad_perm:[1,0,3,2] row_mask:0xf bank_mask:0xf
	s_nop 1
	v_add_f32_dpp v0, v0, v0 quad_perm:[2,3,0,1] row_mask:0xf bank_mask:0xf
	s_nop 1
	v_add_f32_dpp v0, v0, v0 row_half_mirror row_mask:0xf bank_mask:0xf
	s_nop 1
	v_add_f32_dpp v0, v0, v0 row_mirror row_mask:0xf bank_mask:0xf
	s_waitcnt lgkmcnt(0)
	v_mov_b32_e32 v1, v0
	s_nop 1
	v_permlane16_swap_b32_e32 v0, v1
	v_add_f32_e32 v0, v0, v1
	v_fmamk_f32 v0, v0, 0x3c000000, v199
	v_rsq_f32_e32 v0, v0
	v_lshlrev_b32_e32 v1, 16, v144
	v_mul_f32_e32 v2, v3, v0
	v_mul_f32_e32 v3, 0xbfb8aa3b, v1
	v_exp_f32_e32 v3, v3
	v_mul_f32_e32 v2, v113, v2
	v_add_f32_e32 v3, 1.0, v3
	v_rcp_f32_e32 v3, v3
	s_nop 0
	v_mul_f32_e32 v1, v3, v1
	v_mul_f32_e32 v1, v2, v1
	v_cvt_pk_bf16_f32 v1, v1, s0
	ds_write_b16 v138, v1 offset:8960
	v_mul_f32_e32 v2, v19, v0
	v_mul_f32_e32 v2, v130, v2
	v_lshlrev_b32_e32 v1, 16, v145
	v_mul_f32_e32 v3, 0xbfb8aa3b, v1
	v_exp_f32_e32 v3, v3
	s_nop 0
	v_add_f32_e32 v3, 1.0, v3
	v_rcp_f32_e32 v3, v3
	s_nop 0
	v_mul_f32_e32 v1, v3, v1
	v_mul_f32_e32 v1, v2, v1
	v_cvt_pk_bf16_f32 v1, v1, s0
	ds_write_b16 v138, v1 offset:9024
	v_mul_f32_e32 v2, v51, v0
	v_mul_f32_e32 v2, v131, v2
	v_mul_f32_e32 v0, v35, v0
	v_mul_f32_e32 v0, v132, v0
	v_lshlrev_b32_e32 v1, 16, v146
	v_mul_f32_e32 v3, 0xbfb8aa3b, v1
	v_exp_f32_e32 v3, v3
	s_nop 0
	v_add_f32_e32 v3, 1.0, v3
	v_rcp_f32_e32 v3, v3
	s_nop 0
	v_mul_f32_e32 v1, v3, v1
	v_mul_f32_e32 v1, v2, v1
	v_cvt_pk_bf16_f32 v1, v1, s0
	ds_write_b16 v138, v1 offset:9088
	v_lshlrev_b32_e32 v1, 16, v147
	v_mul_f32_e32 v2, 0xbfb8aa3b, v1
	v_exp_f32_e32 v2, v2
	s_nop 0
	v_add_f32_e32 v2, 1.0, v2
	v_rcp_f32_e32 v2, v2
	s_nop 0
	v_mul_f32_e32 v1, v2, v1
	v_mul_f32_e32 v0, v0, v1
	v_cvt_pk_bf16_f32 v0, v0, s0
	ds_write_b16 v138, v0 offset:9152
	v_mul_f32_e32 v0, v20, v20
	v_mul_f32_e32 v1, v36, v36
	v_fmac_f32_e32 v0, v4, v4
	v_fmac_f32_e32 v1, v52, v52
	v_add_f32_e32 v0, v0, v1
	ds_read_u16 v144, v138 offset:2048
	ds_read_u16 v145, v138 offset:2112
	ds_read_u16 v146, v138 offset:2176
	ds_read_u16 v147, v138 offset:2240
	s_nop 1
	v_add_f32_dpp v0, v0, v0 quad_perm:[1,0,3,2] row_mask:0xf bank_mask:0xf
	s_nop 1
	v_add_f32_dpp v0, v0, v0 quad_perm:[2,3,0,1] row_mask:0xf bank_mask:0xf
	s_nop 1
	v_add_f32_dpp v0, v0, v0 row_half_mirror row_mask:0xf bank_mask:0xf
	s_nop 1
	v_add_f32_dpp v0, v0, v0 row_mirror row_mask:0xf bank_mask:0xf
	s_waitcnt lgkmcnt(0)
	v_mov_b32_e32 v1, v0
	s_nop 1
	v_permlane16_swap_b32_e32 v0, v1
	v_add_f32_e32 v0, v0, v1
	v_fmamk_f32 v0, v0, 0x3c000000, v199
	v_rsq_f32_e32 v0, v0
	v_lshlrev_b32_e32 v1, 16, v144
	v_mul_f32_e32 v3, 0xbfb8aa3b, v1
	v_exp_f32_e32 v3, v3
	v_mul_f32_e32 v2, v4, v0
	v_mul_f32_e32 v2, v113, v2
	v_add_f32_e32 v3, 1.0, v3
	v_rcp_f32_e32 v3, v3
	s_nop 0
	v_mul_f32_e32 v1, v3, v1
	v_mul_f32_e32 v1, v2, v1
	v_cvt_pk_bf16_f32 v1, v1, s0
	ds_write_b16 v138, v1 offset:10240
	v_mul_f32_e32 v2, v20, v0
	v_mul_f32_e32 v2, v130, v2
	v_lshlrev_b32_e32 v1, 16, v145
	v_mul_f32_e32 v3, 0xbfb8aa3b, v1
	v_exp_f32_e32 v3, v3
	s_nop 0
	v_add_f32_e32 v3, 1.0, v3
	v_rcp_f32_e32 v3, v3
	s_nop 0
	v_mul_f32_e32 v1, v3, v1
	v_mul_f32_e32 v1, v2, v1
	v_cvt_pk_bf16_f32 v1, v1, s0
	ds_write_b16 v138, v1 offset:10304
	v_mul_f32_e32 v2, v52, v0
	v_mul_f32_e32 v2, v131, v2
	v_mul_f32_e32 v0, v36, v0
	v_mul_f32_e32 v0, v132, v0
	v_lshlrev_b32_e32 v1, 16, v146
	v_mul_f32_e32 v3, 0xbfb8aa3b, v1
	v_exp_f32_e32 v3, v3
	s_nop 0
	v_add_f32_e32 v3, 1.0, v3
	v_rcp_f32_e32 v3, v3
	s_nop 0
	v_mul_f32_e32 v1, v3, v1
	v_mul_f32_e32 v1, v2, v1
	v_cvt_pk_bf16_f32 v1, v1, s0
	ds_write_b16 v138, v1 offset:10368
	v_lshlrev_b32_e32 v1, 16, v147
	v_mul_f32_e32 v2, 0xbfb8aa3b, v1
	v_exp_f32_e32 v2, v2
	s_nop 0
	v_add_f32_e32 v2, 1.0, v2
	v_rcp_f32_e32 v2, v2
	s_nop 0
	v_mul_f32_e32 v1, v2, v1
	v_mul_f32_e32 v0, v0, v1
	v_cvt_pk_bf16_f32 v0, v0, s0
	ds_write_b16 v138, v0 offset:10432
	v_mul_f32_e32 v0, v21, v21
	v_mul_f32_e32 v1, v37, v37
	v_fmac_f32_e32 v0, v5, v5
	v_fmac_f32_e32 v1, v53, v53
	v_add_f32_e32 v0, v0, v1
	ds_read_u16 v144, v138 offset:2304
	ds_read_u16 v145, v138 offset:2368
	ds_read_u16 v146, v138 offset:2432
	ds_read_u16 v147, v138 offset:2496
	s_nop 1
	v_add_f32_dpp v0, v0, v0 quad_perm:[1,0,3,2] row_mask:0xf bank_mask:0xf
	s_nop 1
	v_add_f32_dpp v0, v0, v0 quad_perm:[2,3,0,1] row_mask:0xf bank_mask:0xf
	s_nop 1
	v_add_f32_dpp v0, v0, v0 row_half_mirror row_mask:0xf bank_mask:0xf
	s_nop 1
	v_add_f32_dpp v0, v0, v0 row_mirror row_mask:0xf bank_mask:0xf
	s_waitcnt lgkmcnt(0)
; __device__ __forceinline__ int crow(int r, int hi) { return (r & 3) + 8 * (r >> 2) + 4 * hi; }
; __device__ __forceinline__ float bf2f(unsigned short v) { return __uint_as_float((unsigned)v << 16); }
; __device__ __forceinline__ unsigned f2bf(float f) { return pk2(f, 0.f) & 0xffffu; }
; __device__ __forceinline__ int crow(int r, int hi) { return (r & 3) + 8 * (r >> 2) + 4 * hi; }
; __device__ __forceinline__ void gla_pass_c(LAS unsigned char* ldsl, const bf16_t* __restrict__ proj, const float* __restrict__ Btab, const float* __restrict__ Gst, const float* __restrict__ gout, bf16_t* __restrict__ mixed) {
;     ...
;         for (int i = 0; i < 16; ++i) { const int tr = crow(i, hh);
;             const float tot = half_sum32((o[0][i] * o[0][i] + o[1][i] * o[1][i]) + (o[2][i] * o[2][i] + o[3][i] * o[3][i]));
;             const float rr = __builtin_amdgcn_rsqf(tot * (1.0f / 128.0f) + EPS);
; #pragma unroll
;             for (int dvb = 0; dvb < 4; ++dvb) { const float g = bf2f(Lh[tr * 128 + 32 * dvb + r]);
;                 const float val = o[dvb][i] * rr * gn[dvb] * (g * __builtin_amdgcn_rcpf(1.0f + __expf(-g)));
;                 Lh[(32 + tr) * 128 + 32 * dvb + r] = (bf16_t)f2bf(val); } }
	v_mov_b32_e32 v1, v0
	s_nop 1
	v_permlane16_swap_b32_e32 v0, v1
	v_add_f32_e32 v0, v0, v1
	v_fmamk_f32 v0, v0, 0x3c000000, v199
	v_rsq_f32_e32 v0, v0
	v_lshlrev_b32_e32 v1, 16, v144
	v_mul_f32_e32 v3, 0xbfb8aa3b, v1
	v_exp_f32_e32 v3, v3
	v_mul_f32_e32 v2, v5, v0
	v_mul_f32_e32 v2, v113, v2
	v_add_f32_e32 v3, 1.0, v3
	v_rcp_f32_e32 v3, v3
	s_nop 0
	v_mul_f32_e32 v1, v3, v1
	v_mul_f32_e32 v1, v2, v1
	v_cvt_pk_bf16_f32 v1, v1, s0
	ds_write_b16 v138, v1 offset:10496
	v_mul_f32_e32 v2, v21, v0
	v_mul_f32_e32 v2, v130, v2
	v_lshlrev_b32_e32 v1, 16, v145
	v_mul_f32_e32 v3, 0xbfb8aa3b, v1
	v_exp_f32_e32 v3, v3
	s_nop 0
	v_add_f32_e32 v3, 1.0, v3
	v_rcp_f32_e32 v3, v3
	s_nop 0
	v_mul_f32_e32 v1, v3, v1
	v_mul_f32_e32 v1, v2, v1
	v_cvt_pk_bf16_f32 v1, v1, s0
	ds_write_b16 v138, v1 offset:10560
	v_mul_f32_e32 v2, v53, v0
	v_mul_f32_e32 v2, v131, v2
	v_mul_f32_e32 v0, v37, v0
	v_mul_f32_e32 v0, v132, v0
	v_lshlrev_b32_e32 v1, 16, v146
	v_mul_f32_e32 v3, 0xbfb8aa3b, v1
	v_exp_f32_e32 v3, v3
	s_nop 0
	v_add_f32_e32 v3, 1.0, v3
	v_rcp_f32_e32 v3, v3
	s_nop 0
	v_mul_f32_e32 v1, v3, v1
	v_mul_f32_e32 v1, v2, v1
	v_cvt_pk_bf16_f32 v1, v1, s0
	ds_write_b16 v138, v1 offset:10624
	v_lshlrev_b32_e32 v1, 16, v147
	v_mul_f32_e32 v2, 0xbfb8aa3b, v1
	v_exp_f32_e32 v2, v2
	s_nop 0
	v_add_f32_e32 v2, 1.0, v2
	v_rcp_f32_e32 v2, v2
	s_nop 0
	v_mul_f32_e32 v1, v2, v1
	v_mul_f32_e32 v0, v0, v1
	v_cvt_pk_bf16_f32 v0, v0, s0
	ds_write_b16 v138, v0 offset:10688
	v_mul_f32_e32 v0, v22, v22
	v_mul_f32_e32 v1, v38, v38
	v_fmac_f32_e32 v0, v6, v6
	v_fmac_f32_e32 v1, v54, v54
	v_add_f32_e32 v0, v0, v1
	ds_read_u16 v144, v138 offset:2560
	ds_read_u16 v145, v138 offset:2624
	ds_read_u16 v146, v138 offset:2688
	ds_read_u16 v147, v138 offset:2752
	s_nop 1
	v_add_f32_dpp v0, v0, v0 quad_perm:[1,0,3,2] row_mask:0xf bank_mask:0xf
	s_nop 1
	v_add_f32_dpp v0, v0, v0 quad_perm:[2,3,0,1] row_mask:0xf bank_mask:0xf
	s_nop 1
	v_add_f32_dpp v0, v0, v0 row_half_mirror row_mask:0xf bank_mask:0xf
	s_nop 1
	v_add_f32_dpp v0, v0, v0 row_mirror row_mask:0xf bank_mask:0xf
	s_waitcnt lgkmcnt(0)
	v_mov_b32_e32 v1, v0
	s_nop 1
	v_permlane16_swap_b32_e32 v0, v1
	v_add_f32_e32 v0, v0, v1
	v_fmamk_f32 v0, v0, 0x3c000000, v199
	v_rsq_f32_e32 v0, v0
	v_lshlrev_b32_e32 v1, 16, v144
	v_mul_f32_e32 v3, 0xbfb8aa3b, v1
	v_exp_f32_e32 v3, v3
	v_mul_f32_e32 v2, v6, v0
	v_mul_f32_e32 v2, v113, v2
	v_add_f32_e32 v3, 1.0, v3
	v_rcp_f32_e32 v3, v3
	s_nop 0
	v_mul_f32_e32 v1, v3, v1
	v_mul_f32_e32 v1, v2, v1
	v_cvt_pk_bf16_f32 v1, v1, s0
	ds_write_b16 v138, v1 offset:10752
	v_mul_f32_e32 v2, v22, v0
	v_mul_f32_e32 v2, v130, v2
	v_lshlrev_b32_e32 v1, 16, v145
	v_mul_f32_e32 v3, 0xbfb8aa3b, v1
	v_exp_f32_e32 v3, v3
	s_nop 0
	v_add_f32_e32 v3, 1.0, v3
	v_rcp_f32_e32 v3, v3
	s_nop 0
	v_mul_f32_e32 v1, v3, v1
	v_mul_f32_e32 v1, v2, v1
	v_cvt_pk_bf16_f32 v1, v1, s0
	ds_write_b16 v138, v1 offset:10816
	v_mul_f32_e32 v2, v54, v0
	v_mul_f32_e32 v2, v131, v2
	v_mul_f32_e32 v0, v38, v0
	v_mul_f32_e32 v0, v132, v0
	v_lshlrev_b32_e32 v1, 16, v146
	v_mul_f32_e32 v3, 0xbfb8aa3b, v1
	v_exp_f32_e32 v3, v3
	s_nop 0
	v_add_f32_e32 v3, 1.0, v3
	v_rcp_f32_e32 v3, v3
	s_nop 0
	v_mul_f32_e32 v1, v3, v1
	v_mul_f32_e32 v1, v2, v1
	v_cvt_pk_bf16_f32 v1, v1, s0
	ds_write_b16 v138, v1 offset:10880
	v_lshlrev_b32_e32 v1, 16, v147
	v_mul_f32_e32 v2, 0xbfb8aa3b, v1
	v_exp_f32_e32 v2, v2
	s_nop 0
	v_add_f32_e32 v2, 1.0, v2
	v_rcp_f32_e32 v2, v2
	s_nop 0
	v_mul_f32_e32 v1, v2, v1
	v_mul_f32_e32 v0, v0, v1
	v_cvt_pk_bf16_f32 v0, v0, s0
	ds_write_b16 v138, v0 offset:10944
	v_mul_f32_e32 v0, v23, v23
	v_mul_f32_e32 v1, v39, v39
	v_fmac_f32_e32 v0, v7, v7
	v_fmac_f32_e32 v1, v55, v55
	v_add_f32_e32 v0, v0, v1
	ds_read_u16 v144, v138 offset:2816
	ds_read_u16 v145, v138 offset:2880
	ds_read_u16 v146, v138 offset:2944
	ds_read_u16 v147, v138 offset:3008
	s_nop 1
	v_add_f32_dpp v0, v0, v0 quad_perm:[1,0,3,2] row_mask:0xf bank_mask:0xf
	s_nop 1
	v_add_f32_dpp v0, v0, v0 quad_perm:[2,3,0,1] row_mask:0xf bank_mask:0xf
	s_nop 1
	v_add_f32_dpp v0, v0, v0 row_half_mirror row_mask:0xf bank_mask:0xf
	s_nop 1
	v_add_f32_dpp v0, v0, v0 row_mirror row_mask:0xf bank_mask:0xf
	s_waitcnt lgkmcnt(0)
	v_mov_b32_e32 v1, v0
	s_nop 1
	v_permlane16_swap_b32_e32 v0, v1
	v_add_f32_e32 v0, v0, v1
	v_fmamk_f32 v0, v0, 0x3c000000, v199
	v_rsq_f32_e32 v0, v0
	v_lshlrev_b32_e32 v1, 16, v144
	v_mul_f32_e32 v3, 0xbfb8aa3b, v1
	v_exp_f32_e32 v3, v3
	v_mul_f32_e32 v2, v7, v0
	v_mul_f32_e32 v2, v113, v2
	v_add_f32_e32 v3, 1.0, v3
	v_rcp_f32_e32 v3, v3
	s_nop 0
	v_mul_f32_e32 v1, v3, v1
	v_mul_f32_e32 v1, v2, v1
	v_cvt_pk_bf16_f32 v1, v1, s0
	ds_write_b16 v138, v1 offset:11008
	v_mul_f32_e32 v2, v23, v0
	v_mul_f32_e32 v2, v130, v2
	v_lshlrev_b32_e32 v1, 16, v145
	v_mul_f32_e32 v3, 0xbfb8aa3b, v1
	v_exp_f32_e32 v3, v3
	s_nop 0
	v_add_f32_e32 v3, 1.0, v3
	v_rcp_f32_e32 v3, v3
	s_nop 0
	v_mul_f32_e32 v1, v3, v1
	v_mul_f32_e32 v1, v2, v1
	v_cvt_pk_bf16_f32 v1, v1, s0
	ds_write_b16 v138, v1 offset:11072
	v_mul_f32_e32 v2, v55, v0
	v_mul_f32_e32 v2, v131, v2
	v_mul_f32_e32 v0, v39, v0
	v_mul_f32_e32 v0, v132, v0
	v_lshlrev_b32_e32 v1, 16, v146
	v_mul_f32_e32 v3, 0xbfb8aa3b, v1
	v_exp_f32_e32 v3, v3
	s_nop 0
	v_add_f32_e32 v3, 1.0, v3
	v_rcp_f32_e32 v3, v3
	s_nop 0
	v_mul_f32_e32 v1, v3, v1
	v_mul_f32_e32 v1, v2, v1
	v_cvt_pk_bf16_f32 v1, v1, s0
	ds_write_b16 v138, v1 offset:11136
	v_lshlrev_b32_e32 v1, 16, v147
	v_mul_f32_e32 v2, 0xbfb8aa3b, v1
	v_exp_f32_e32 v2, v2
	s_nop 0
	v_add_f32_e32 v2, 1.0, v2
	v_rcp_f32_e32 v2, v2
	s_nop 0
	v_mul_f32_e32 v1, v2, v1
	v_mul_f32_e32 v0, v0, v1
	v_cvt_pk_bf16_f32 v0, v0, s0
	ds_write_b16 v138, v0 offset:11200
	v_mul_f32_e32 v0, v24, v24
	v_mul_f32_e32 v1, v40, v40
	v_fmac_f32_e32 v0, v8, v8
	v_fmac_f32_e32 v1, v56, v56
	v_add_f32_e32 v0, v0, v1
	ds_read_u16 v144, v138 offset:4096
	ds_read_u16 v145, v138 offset:4160
	ds_read_u16 v146, v138 offset:4224
	ds_read_u16 v147, v138 offset:4288
	s_nop 1
	v_add_f32_dpp v0, v0, v0 quad_perm:[1,0,3,2] row_mask:0xf bank_mask:0xf
	s_nop 1
	v_add_f32_dpp v0, v0, v0 quad_perm:[2,3,0,1] row_mask:0xf bank_mask:0xf
	s_nop 1
	v_add_f32_dpp v0, v0, v0 row_half_mirror row_mask:0xf bank_mask:0xf
	s_nop 1
	v_add_f32_dpp v0, v0, v0 row_mirror row_mask:0xf bank_mask:0xf
	s_waitcnt lgkmcnt(0)
; __device__ __forceinline__ int crow(int r, int hi) { return (r & 3) + 8 * (r >> 2) + 4 * hi; }
; __device__ __forceinline__ float bf2f(unsigned short v) { return __uint_as_float((unsigned)v << 16); }
; __device__ __forceinline__ unsigned f2bf(float f) { return pk2(f, 0.f) & 0xffffu; }
; __device__ __forceinline__ int crow(int r, int hi) { return (r & 3) + 8 * (r >> 2) + 4 * hi; }
; __device__ __forceinline__ void gla_pass_c(LAS unsigned char* ldsl, const bf16_t* __restrict__ proj, const float* __restrict__ Btab, const float* __restrict__ Gst, const float* __restrict__ gout, bf16_t* __restrict__ mixed) {
;     ...
;         for (int i = 0; i < 16; ++i) { const int tr = crow(i, hh);
;             const float tot = half_sum32((o[0][i] * o[0][i] + o[1][i] * o[1][i]) + (o[2][i] * o[2][i] + o[3][i] * o[3][i]));
;             const float rr = __builtin_amdgcn_rsqf(tot * (1.0f / 128.0f) + EPS);
; #pragma unroll
;             for (int dvb = 0; dvb < 4; ++dvb) { const float g = bf2f(Lh[tr * 128 + 32 * dvb + r]);
;                 const float val = o[dvb][i] * rr * gn[dvb] * (g * __builtin_amdgcn_rcpf(1.0f + __expf(-g)));
;                 Lh[(32 + tr) * 128 + 32 * dvb + r] = (bf16_t)f2bf(val); } }
	v_mov_b32_e32 v1, v0
	s_nop 1
	v_permlane16_swap_b32_e32 v0, v1
	v_add_f32_e32 v0, v0, v1
	v_fmamk_f32 v0, v0, 0x3c000000, v199
	v_rsq_f32_e32 v0, v0
	v_lshlrev_b32_e32 v1, 16, v144
	v_mul_f32_e32 v3, 0xbfb8aa3b, v1
	v_exp_f32_e32 v3, v3
	v_mul_f32_e32 v2, v8, v0
	v_mul_f32_e32 v2, v113, v2
	v_add_f32_e32 v3, 1.0, v3
	v_rcp_f32_e32 v3, v3
	s_nop 0
	v_mul_f32_e32 v1, v3, v1
	v_mul_f32_e32 v1, v2, v1
	v_cvt_pk_bf16_f32 v1, v1, s0
	ds_write_b16 v138, v1 offset:12288
	v_mul_f32_e32 v2, v24, v0
	v_mul_f32_e32 v2, v130, v2
	v_lshlrev_b32_e32 v1, 16, v145
	v_mul_f32_e32 v3, 0xbfb8aa3b, v1
	v_exp_f32_e32 v3, v3
	s_nop 0
	v_add_f32_e32 v3, 1.0, v3
	v_rcp_f32_e32 v3, v3
	s_nop 0
	v_mul_f32_e32 v1, v3, v1
	v_mul_f32_e32 v1, v2, v1
	v_cvt_pk_bf16_f32 v1, v1, s0
	ds_write_b16 v138, v1 offset:12352
	v_mul_f32_e32 v2, v56, v0
	v_mul_f32_e32 v2, v131, v2
	v_mul_f32_e32 v0, v40, v0
	v_mul_f32_e32 v0, v132, v0
	v_lshlrev_b32_e32 v1, 16, v146
	v_mul_f32_e32 v3, 0xbfb8aa3b, v1
	v_exp_f32_e32 v3, v3
	s_nop 0
	v_add_f32_e32 v3, 1.0, v3
	v_rcp_f32_e32 v3, v3
	s_nop 0
	v_mul_f32_e32 v1, v3, v1
	v_mul_f32_e32 v1, v2, v1
	v_cvt_pk_bf16_f32 v1, v1, s0
	ds_write_b16 v138, v1 offset:12416
	v_lshlrev_b32_e32 v1, 16, v147
	v_mul_f32_e32 v2, 0xbfb8aa3b, v1
	v_exp_f32_e32 v2, v2
	s_nop 0
	v_add_f32_e32 v2, 1.0, v2
	v_rcp_f32_e32 v2, v2
	s_nop 0
	v_mul_f32_e32 v1, v2, v1
	v_mul_f32_e32 v0, v0, v1
	v_cvt_pk_bf16_f32 v0, v0, s0
	ds_write_b16 v138, v0 offset:12480
	v_mul_f32_e32 v0, v25, v25
	v_mul_f32_e32 v1, v41, v41
	v_fmac_f32_e32 v0, v9, v9
	v_fmac_f32_e32 v1, v57, v57
	v_add_f32_e32 v0, v0, v1
	ds_read_u16 v144, v138 offset:4352
	ds_read_u16 v145, v138 offset:4416
	ds_read_u16 v146, v138 offset:4480
	ds_read_u16 v147, v138 offset:4544
	s_nop 1
	v_add_f32_dpp v0, v0, v0 quad_perm:[1,0,3,2] row_mask:0xf bank_mask:0xf
	s_nop 1
	v_add_f32_dpp v0, v0, v0 quad_perm:[2,3,0,1] row_mask:0xf bank_mask:0xf
	s_nop 1
	v_add_f32_dpp v0, v0, v0 row_half_mirror row_mask:0xf bank_mask:0xf
	s_nop 1
	v_add_f32_dpp v0, v0, v0 row_mirror row_mask:0xf bank_mask:0xf
	s_waitcnt lgkmcnt(0)
	v_mov_b32_e32 v1, v0
	s_nop 1
	v_permlane16_swap_b32_e32 v0, v1
	v_add_f32_e32 v0, v0, v1
	v_fmamk_f32 v0, v0, 0x3c000000, v199
	v_rsq_f32_e32 v0, v0
	v_lshlrev_b32_e32 v1, 16, v144
	v_mul_f32_e32 v3, 0xbfb8aa3b, v1
	v_exp_f32_e32 v3, v3
	v_mul_f32_e32 v2, v9, v0
	v_mul_f32_e32 v2, v113, v2
	v_add_f32_e32 v3, 1.0, v3
	v_rcp_f32_e32 v3, v3
	s_nop 0
	v_mul_f32_e32 v1, v3, v1
	v_mul_f32_e32 v1, v2, v1
	v_cvt_pk_bf16_f32 v1, v1, s0
	ds_write_b16 v138, v1 offset:12544
	v_mul_f32_e32 v2, v25, v0
	v_mul_f32_e32 v2, v130, v2
	v_lshlrev_b32_e32 v1, 16, v145
	v_mul_f32_e32 v3, 0xbfb8aa3b, v1
	v_exp_f32_e32 v3, v3
	s_nop 0
	v_add_f32_e32 v3, 1.0, v3
	v_rcp_f32_e32 v3, v3
	s_nop 0
	v_mul_f32_e32 v1, v3, v1
	v_mul_f32_e32 v1, v2, v1
	v_cvt_pk_bf16_f32 v1, v1, s0
	ds_write_b16 v138, v1 offset:12608
	v_mul_f32_e32 v2, v57, v0
	v_mul_f32_e32 v2, v131, v2
	v_mul_f32_e32 v0, v41, v0
	v_mul_f32_e32 v0, v132, v0
	v_lshlrev_b32_e32 v1, 16, v146
	v_mul_f32_e32 v3, 0xbfb8aa3b, v1
	v_exp_f32_e32 v3, v3
	s_nop 0
	v_add_f32_e32 v3, 1.0, v3
	v_rcp_f32_e32 v3, v3
	s_nop 0
	v_mul_f32_e32 v1, v3, v1
	v_mul_f32_e32 v1, v2, v1
	v_cvt_pk_bf16_f32 v1, v1, s0
	ds_write_b16 v138, v1 offset:12672
	v_lshlrev_b32_e32 v1, 16, v147
	v_mul_f32_e32 v2, 0xbfb8aa3b, v1
	v_exp_f32_e32 v2, v2
	s_nop 0
	v_add_f32_e32 v2, 1.0, v2
	v_rcp_f32_e32 v2, v2
	s_nop 0
	v_mul_f32_e32 v1, v2, v1
	v_mul_f32_e32 v0, v0, v1
	v_cvt_pk_bf16_f32 v0, v0, s0
	ds_write_b16 v138, v0 offset:12736
	v_mul_f32_e32 v0, v26, v26
	v_mul_f32_e32 v1, v42, v42
	v_fmac_f32_e32 v0, v10, v10
	v_fmac_f32_e32 v1, v58, v58
	v_add_f32_e32 v0, v0, v1
	ds_read_u16 v144, v138 offset:4608
	ds_read_u16 v145, v138 offset:4672
	ds_read_u16 v146, v138 offset:4736
	ds_read_u16 v147, v138 offset:4800
	s_nop 1
	v_add_f32_dpp v0, v0, v0 quad_perm:[1,0,3,2] row_mask:0xf bank_mask:0xf
	s_nop 1
	v_add_f32_dpp v0, v0, v0 quad_perm:[2,3,0,1] row_mask:0xf bank_mask:0xf
	s_nop 1
	v_add_f32_dpp v0, v0, v0 row_half_mirror row_mask:0xf bank_mask:0xf
	s_nop 1
	v_add_f32_dpp v0, v0, v0 row_mirror row_mask:0xf bank_mask:0xf
	s_waitcnt lgkmcnt(0)
	v_mov_b32_e32 v1, v0
	s_nop 1
	v_permlane16_swap_b32_e32 v0, v1
	v_add_f32_e32 v0, v0, v1
	v_fmamk_f32 v0, v0, 0x3c000000, v199
	v_rsq_f32_e32 v0, v0
	v_lshlrev_b32_e32 v1, 16, v144
	v_mul_f32_e32 v3, 0xbfb8aa3b, v1
	v_exp_f32_e32 v3, v3
	v_mul_f32_e32 v2, v10, v0
	v_mul_f32_e32 v2, v113, v2
	v_add_f32_e32 v3, 1.0, v3
	v_rcp_f32_e32 v3, v3
	s_nop 0
	v_mul_f32_e32 v1, v3, v1
	v_mul_f32_e32 v1, v2, v1
	v_cvt_pk_bf16_f32 v1, v1, s0
	ds_write_b16 v138, v1 offset:12800
	v_mul_f32_e32 v2, v26, v0
	v_mul_f32_e32 v2, v130, v2
	v_lshlrev_b32_e32 v1, 16, v145
	v_mul_f32_e32 v3, 0xbfb8aa3b, v1
	v_exp_f32_e32 v3, v3
	s_nop 0
	v_add_f32_e32 v3, 1.0, v3
	v_rcp_f32_e32 v3, v3
	s_nop 0
	v_mul_f32_e32 v1, v3, v1
	v_mul_f32_e32 v1, v2, v1
	v_cvt_pk_bf16_f32 v1, v1, s0
	ds_write_b16 v138, v1 offset:12864
	v_mul_f32_e32 v2, v58, v0
	v_mul_f32_e32 v2, v131, v2
	v_mul_f32_e32 v0, v42, v0
	v_mul_f32_e32 v0, v132, v0
	v_lshlrev_b32_e32 v1, 16, v146
	v_mul_f32_e32 v3, 0xbfb8aa3b, v1
	v_exp_f32_e32 v3, v3
	s_nop 0
	v_add_f32_e32 v3, 1.0, v3
	v_rcp_f32_e32 v3, v3
	s_nop 0
	v_mul_f32_e32 v1, v3, v1
	v_mul_f32_e32 v1, v2, v1
	v_cvt_pk_bf16_f32 v1, v1, s0
	ds_write_b16 v138, v1 offset:12928
	v_lshlrev_b32_e32 v1, 16, v147
	v_mul_f32_e32 v2, 0xbfb8aa3b, v1
	v_exp_f32_e32 v2, v2
	s_nop 0
	v_add_f32_e32 v2, 1.0, v2
	v_rcp_f32_e32 v2, v2
	s_nop 0
	v_mul_f32_e32 v1, v2, v1
	v_mul_f32_e32 v0, v0, v1
	v_cvt_pk_bf16_f32 v0, v0, s0
	ds_write_b16 v138, v0 offset:12992
	v_mul_f32_e32 v0, v27, v27
	v_mul_f32_e32 v1, v43, v43
	v_fmac_f32_e32 v0, v11, v11
	v_fmac_f32_e32 v1, v59, v59
	v_add_f32_e32 v0, v0, v1
	ds_read_u16 v144, v138 offset:4864
	ds_read_u16 v145, v138 offset:4928
	ds_read_u16 v146, v138 offset:4992
	ds_read_u16 v147, v138 offset:5056
	s_nop 1
	v_add_f32_dpp v0, v0, v0 quad_perm:[1,0,3,2] row_mask:0xf bank_mask:0xf
	s_nop 1
	v_add_f32_dpp v0, v0, v0 quad_perm:[2,3,0,1] row_mask:0xf bank_mask:0xf
	s_nop 1
	v_add_f32_dpp v0, v0, v0 row_half_mirror row_mask:0xf bank_mask:0xf
	s_nop 1
	v_add_f32_dpp v0, v0, v0 row_mirror row_mask:0xf bank_mask:0xf
	s_waitcnt lgkmcnt(0)
; __device__ __forceinline__ int crow(int r, int hi) { return (r & 3) + 8 * (r >> 2) + 4 * hi; }
; __device__ __forceinline__ float bf2f(unsigned short v) { return __uint_as_float((unsigned)v << 16); }
; __device__ __forceinline__ unsigned f2bf(float f) { return pk2(f, 0.f) & 0xffffu; }
; __device__ __forceinline__ int crow(int r, int hi) { return (r & 3) + 8 * (r >> 2) + 4 * hi; }
; __device__ __forceinline__ void gla_pass_c(LAS unsigned char* ldsl, const bf16_t* __restrict__ proj, const float* __restrict__ Btab, const float* __restrict__ Gst, const float* __restrict__ gout, bf16_t* __restrict__ mixed) {
;     ...
;         for (int i = 0; i < 16; ++i) { const int tr = crow(i, hh);
;             const float tot = half_sum32((o[0][i] * o[0][i] + o[1][i] * o[1][i]) + (o[2][i] * o[2][i] + o[3][i] * o[3][i]));
;             const float rr = __builtin_amdgcn_rsqf(tot * (1.0f / 128.0f) + EPS);
; #pragma unroll
;             for (int dvb = 0; dvb < 4; ++dvb) { const float g = bf2f(Lh[tr * 128 + 32 * dvb + r]);
;                 const float val = o[dvb][i] * rr * gn[dvb] * (g * __builtin_amdgcn_rcpf(1.0f + __expf(-g)));
;                 Lh[(32 + tr) * 128 + 32 * dvb + r] = (bf16_t)f2bf(val); } }
	v_mov_b32_e32 v1, v0
	s_nop 1
	v_permlane16_swap_b32_e32 v0, v1
	v_add_f32_e32 v0, v0, v1
	v_fmamk_f32 v0, v0, 0x3c000000, v199
	v_rsq_f32_e32 v0, v0
	v_lshlrev_b32_e32 v1, 16, v144
	v_mul_f32_e32 v3, 0xbfb8aa3b, v1
	v_exp_f32_e32 v3, v3
	v_mul_f32_e32 v2, v11, v0
	v_mul_f32_e32 v2, v113, v2
	v_add_f32_e32 v3, 1.0, v3
	v_rcp_f32_e32 v3, v3
	s_nop 0
	v_mul_f32_e32 v1, v3, v1
	v_mul_f32_e32 v1, v2, v1
	v_cvt_pk_bf16_f32 v1, v1, s0
	ds_write_b16 v138, v1 offset:13056
	v_mul_f32_e32 v2, v27, v0
	v_mul_f32_e32 v2, v130, v2
	v_lshlrev_b32_e32 v1, 16, v145
	v_mul_f32_e32 v3, 0xbfb8aa3b, v1
	v_exp_f32_e32 v3, v3
	s_nop 0
	v_add_f32_e32 v3, 1.0, v3
	v_rcp_f32_e32 v3, v3
	s_nop 0
	v_mul_f32_e32 v1, v3, v1
	v_mul_f32_e32 v1, v2, v1
	v_cvt_pk_bf16_f32 v1, v1, s0
	ds_write_b16 v138, v1 offset:13120
	v_mul_f32_e32 v2, v59, v0
	v_mul_f32_e32 v2, v131, v2
	v_mul_f32_e32 v0, v43, v0
	v_mul_f32_e32 v0, v132, v0
	v_lshlrev_b32_e32 v1, 16, v146
	v_mul_f32_e32 v3, 0xbfb8aa3b, v1
	v_exp_f32_e32 v3, v3
	s_nop 0
	v_add_f32_e32 v3, 1.0, v3
	v_rcp_f32_e32 v3, v3
	s_nop 0
	v_mul_f32_e32 v1, v3, v1
	v_mul_f32_e32 v1, v2, v1
	v_cvt_pk_bf16_f32 v1, v1, s0
	ds_write_b16 v138, v1 offset:13184
	v_lshlrev_b32_e32 v1, 16, v147
	v_mul_f32_e32 v2, 0xbfb8aa3b, v1
	v_exp_f32_e32 v2, v2
	s_nop 0
	v_add_f32_e32 v2, 1.0, v2
	v_rcp_f32_e32 v2, v2
	s_nop 0
	v_mul_f32_e32 v1, v2, v1
	v_mul_f32_e32 v0, v0, v1
	v_cvt_pk_bf16_f32 v0, v0, s0
	ds_write_b16 v138, v0 offset:13248
	v_mul_f32_e32 v0, v28, v28
	v_mul_f32_e32 v1, v44, v44
	v_fmac_f32_e32 v0, v12, v12
	v_fmac_f32_e32 v1, v60, v60
	v_add_f32_e32 v0, v0, v1
	ds_read_u16 v144, v138 offset:6144
	ds_read_u16 v145, v138 offset:6208
	ds_read_u16 v146, v138 offset:6272
	ds_read_u16 v147, v138 offset:6336
	s_nop 1
	v_add_f32_dpp v0, v0, v0 quad_perm:[1,0,3,2] row_mask:0xf bank_mask:0xf
	s_nop 1
	v_add_f32_dpp v0, v0, v0 quad_perm:[2,3,0,1] row_mask:0xf bank_mask:0xf
	s_nop 1
	v_add_f32_dpp v0, v0, v0 row_half_mirror row_mask:0xf bank_mask:0xf
	s_nop 1
	v_add_f32_dpp v0, v0, v0 row_mirror row_mask:0xf bank_mask:0xf
	s_waitcnt lgkmcnt(0)
	v_mov_b32_e32 v1, v0
	s_nop 1
	v_permlane16_swap_b32_e32 v0, v1
	v_add_f32_e32 v0, v0, v1
	v_fmamk_f32 v0, v0, 0x3c000000, v199
	v_rsq_f32_e32 v0, v0
	v_lshlrev_b32_e32 v1, 16, v144
	v_mul_f32_e32 v3, 0xbfb8aa3b, v1
	v_exp_f32_e32 v3, v3
	v_mul_f32_e32 v2, v12, v0
	v_mul_f32_e32 v2, v113, v2
	v_add_f32_e32 v3, 1.0, v3
	v_rcp_f32_e32 v3, v3
	s_nop 0
	v_mul_f32_e32 v1, v3, v1
	v_mul_f32_e32 v1, v2, v1
	v_cvt_pk_bf16_f32 v1, v1, s0
	ds_write_b16 v138, v1 offset:14336
	v_mul_f32_e32 v2, v28, v0
	v_mul_f32_e32 v2, v130, v2
	v_lshlrev_b32_e32 v1, 16, v145
	v_mul_f32_e32 v3, 0xbfb8aa3b, v1
	v_exp_f32_e32 v3, v3
	s_nop 0
	v_add_f32_e32 v3, 1.0, v3
	v_rcp_f32_e32 v3, v3
	s_nop 0
	v_mul_f32_e32 v1, v3, v1
	v_mul_f32_e32 v1, v2, v1
	v_cvt_pk_bf16_f32 v1, v1, s0
	ds_write_b16 v138, v1 offset:14400
	v_mul_f32_e32 v2, v60, v0
	v_mul_f32_e32 v2, v131, v2
	v_mul_f32_e32 v0, v44, v0
	v_mul_f32_e32 v0, v132, v0
	v_lshlrev_b32_e32 v1, 16, v146
	v_mul_f32_e32 v3, 0xbfb8aa3b, v1
	v_exp_f32_e32 v3, v3
	s_nop 0
	v_add_f32_e32 v3, 1.0, v3
	v_rcp_f32_e32 v3, v3
	s_nop 0
	v_mul_f32_e32 v1, v3, v1
	v_mul_f32_e32 v1, v2, v1
	v_cvt_pk_bf16_f32 v1, v1, s0
	ds_write_b16 v138, v1 offset:14464
	v_lshlrev_b32_e32 v1, 16, v147
	v_mul_f32_e32 v2, 0xbfb8aa3b, v1
	v_exp_f32_e32 v2, v2
	s_nop 0
	v_add_f32_e32 v2, 1.0, v2
	v_rcp_f32_e32 v2, v2
	s_nop 0
	v_mul_f32_e32 v1, v2, v1
	v_mul_f32_e32 v0, v0, v1
	v_cvt_pk_bf16_f32 v0, v0, s0
	ds_write_b16 v138, v0 offset:14528
	v_mul_f32_e32 v0, v29, v29
	v_mul_f32_e32 v1, v45, v45
	v_fmac_f32_e32 v0, v13, v13
	v_fmac_f32_e32 v1, v61, v61
	v_add_f32_e32 v0, v0, v1
	ds_read_u16 v144, v138 offset:6400
	ds_read_u16 v145, v138 offset:6464
	ds_read_u16 v146, v138 offset:6528
	ds_read_u16 v147, v138 offset:6592
	s_nop 1
	v_add_f32_dpp v0, v0, v0 quad_perm:[1,0,3,2] row_mask:0xf bank_mask:0xf
	s_nop 1
	v_add_f32_dpp v0, v0, v0 quad_perm:[2,3,0,1] row_mask:0xf bank_mask:0xf
	s_nop 1
	v_add_f32_dpp v0, v0, v0 row_half_mirror row_mask:0xf bank_mask:0xf
	s_nop 1
	v_add_f32_dpp v0, v0, v0 row_mirror row_mask:0xf bank_mask:0xf
	s_waitcnt lgkmcnt(0)
	v_mov_b32_e32 v1, v0
	s_nop 1
	v_permlane16_swap_b32_e32 v0, v1
	v_add_f32_e32 v0, v0, v1
	v_fmamk_f32 v0, v0, 0x3c000000, v199
	v_rsq_f32_e32 v0, v0
	v_lshlrev_b32_e32 v1, 16, v144
	v_mul_f32_e32 v3, 0xbfb8aa3b, v1
	v_exp_f32_e32 v3, v3
	v_mul_f32_e32 v2, v13, v0
	v_mul_f32_e32 v2, v113, v2
	v_add_f32_e32 v3, 1.0, v3
	v_rcp_f32_e32 v3, v3
	s_nop 0
	v_mul_f32_e32 v1, v3, v1
	v_mul_f32_e32 v1, v2, v1
	v_cvt_pk_bf16_f32 v1, v1, s0
	ds_write_b16 v138, v1 offset:14592
	v_mul_f32_e32 v2, v29, v0
	v_mul_f32_e32 v2, v130, v2
	v_lshlrev_b32_e32 v1, 16, v145
	v_mul_f32_e32 v3, 0xbfb8aa3b, v1
	v_exp_f32_e32 v3, v3
	s_nop 0
	v_add_f32_e32 v3, 1.0, v3
	v_rcp_f32_e32 v3, v3
	s_nop 0
	v_mul_f32_e32 v1, v3, v1
	v_mul_f32_e32 v1, v2, v1
	v_cvt_pk_bf16_f32 v1, v1, s0
	ds_write_b16 v138, v1 offset:14656
	v_mul_f32_e32 v2, v61, v0
	v_mul_f32_e32 v2, v131, v2
	v_mul_f32_e32 v0, v45, v0
	v_mul_f32_e32 v0, v132, v0
	v_lshlrev_b32_e32 v1, 16, v146
	v_mul_f32_e32 v3, 0xbfb8aa3b, v1
	v_exp_f32_e32 v3, v3
	s_nop 0
	v_add_f32_e32 v3, 1.0, v3
	v_rcp_f32_e32 v3, v3
	s_nop 0
	v_mul_f32_e32 v1, v3, v1
	v_mul_f32_e32 v1, v2, v1
	v_cvt_pk_bf16_f32 v1, v1, s0
	ds_write_b16 v138, v1 offset:14720
	v_lshlrev_b32_e32 v1, 16, v147
	v_mul_f32_e32 v2, 0xbfb8aa3b, v1
	v_exp_f32_e32 v2, v2
	s_nop 0
	v_add_f32_e32 v2, 1.0, v2
	v_rcp_f32_e32 v2, v2
	s_nop 0
	v_mul_f32_e32 v1, v2, v1
	v_mul_f32_e32 v0, v0, v1
	v_cvt_pk_bf16_f32 v0, v0, s0
	ds_write_b16 v138, v0 offset:14784
	v_mul_f32_e32 v0, v30, v30
	v_mul_f32_e32 v1, v46, v46
	v_fmac_f32_e32 v0, v14, v14
	v_fmac_f32_e32 v1, v62, v62
	v_add_f32_e32 v0, v0, v1
	ds_read_u16 v144, v138 offset:6656
	ds_read_u16 v145, v138 offset:6720
	ds_read_u16 v146, v138 offset:6784
	ds_read_u16 v147, v138 offset:6848
	s_nop 1
	v_add_f32_dpp v0, v0, v0 quad_perm:[1,0,3,2] row_mask:0xf bank_mask:0xf
	s_nop 1
	v_add_f32_dpp v0, v0, v0 quad_perm:[2,3,0,1] row_mask:0xf bank_mask:0xf
	s_nop 1
	v_add_f32_dpp v0, v0, v0 row_half_mirror row_mask:0xf bank_mask:0xf
	s_nop 1
	v_add_f32_dpp v0, v0, v0 row_mirror row_mask:0xf bank_mask:0xf
	s_waitcnt lgkmcnt(0)
; #define LAS __attribute__((address_space(3)))
; __device__ __forceinline__ int crow(int r, int hi) { return (r & 3) + 8 * (r >> 2) + 4 * hi; }
; __device__ __forceinline__ float bf2f(unsigned short v) { return __uint_as_float((unsigned)v << 16); }
; __device__ __forceinline__ unsigned f2bf(float f) { return pk2(f, 0.f) & 0xffffu; }
; __device__ __forceinline__ int crow(int r, int hi) { return (r & 3) + 8 * (r >> 2) + 4 * hi; }
; __device__ __forceinline__ void gla_pass_c(LAS unsigned char* ldsl, const bf16_t* __restrict__ proj, const float* __restrict__ Btab, const float* __restrict__ Gst, const float* __restrict__ gout, bf16_t* __restrict__ mixed) {
;     ...
;         for (int i = 0; i < 16; ++i) { const int tr = crow(i, hh);
;             const float tot = half_sum32((o[0][i] * o[0][i] + o[1][i] * o[1][i]) + (o[2][i] * o[2][i] + o[3][i] * o[3][i]));
;             const float rr = __builtin_amdgcn_rsqf(tot * (1.0f / 128.0f) + EPS);
; #pragma unroll
;             for (int dvb = 0; dvb < 4; ++dvb) { const float g = bf2f(Lh[tr * 128 + 32 * dvb + r]);
;                 const float val = o[dvb][i] * rr * gn[dvb] * (g * __builtin_amdgcn_rcpf(1.0f + __expf(-g)));
;                 Lh[(32 + tr) * 128 + 32 * dvb + r] = (bf16_t)f2bf(val); } }
;         { bf16_t* mp = mixed + (row0 + 32 * tb + crw) * DM + h * 128 + ccl * 8;
; #pragma unroll
;           for (int i = 0; i < 8; ++i) *(u32x4*)(mp + (size_t)(4 * i) * DM) = *(const LAS u32x4*)(Lw + (32 + 4 * i + crw) * 256 + ccl * 16); }
	v_mov_b32_e32 v1, v0
	s_nop 1
	v_permlane16_swap_b32_e32 v0, v1
	v_add_f32_e32 v0, v0, v1
	v_fmamk_f32 v0, v0, 0x3c000000, v199
	v_rsq_f32_e32 v0, v0
	v_lshlrev_b32_e32 v1, 16, v144
	v_mul_f32_e32 v3, 0xbfb8aa3b, v1
	v_exp_f32_e32 v3, v3
	v_mul_f32_e32 v2, v14, v0
	v_mul_f32_e32 v2, v113, v2
	v_add_f32_e32 v3, 1.0, v3
	v_rcp_f32_e32 v3, v3
	s_nop 0
	v_mul_f32_e32 v1, v3, v1
	v_mul_f32_e32 v1, v2, v1
	v_cvt_pk_bf16_f32 v1, v1, s0
	ds_write_b16 v138, v1 offset:14848
	v_mul_f32_e32 v2, v30, v0
	v_mul_f32_e32 v2, v130, v2
	v_lshlrev_b32_e32 v1, 16, v145
	v_mul_f32_e32 v3, 0xbfb8aa3b, v1
	v_exp_f32_e32 v3, v3
	s_nop 0
	v_add_f32_e32 v3, 1.0, v3
	v_rcp_f32_e32 v3, v3
	s_nop 0
	v_mul_f32_e32 v1, v3, v1
	v_mul_f32_e32 v1, v2, v1
	v_cvt_pk_bf16_f32 v1, v1, s0
	ds_write_b16 v138, v1 offset:14912
	v_mul_f32_e32 v2, v62, v0
	v_mul_f32_e32 v2, v131, v2
	v_mul_f32_e32 v0, v46, v0
	v_mul_f32_e32 v0, v132, v0
	v_lshlrev_b32_e32 v1, 16, v146
	v_mul_f32_e32 v3, 0xbfb8aa3b, v1
	v_exp_f32_e32 v3, v3
	s_nop 0
	v_add_f32_e32 v3, 1.0, v3
	v_rcp_f32_e32 v3, v3
	s_nop 0
	v_mul_f32_e32 v1, v3, v1
	v_mul_f32_e32 v1, v2, v1
	v_cvt_pk_bf16_f32 v1, v1, s0
	ds_write_b16 v138, v1 offset:14976
	v_lshlrev_b32_e32 v1, 16, v147
	v_mul_f32_e32 v2, 0xbfb8aa3b, v1
	v_exp_f32_e32 v2, v2
	s_nop 0
	v_add_f32_e32 v2, 1.0, v2
	v_rcp_f32_e32 v2, v2
	s_nop 0
	v_mul_f32_e32 v1, v2, v1
	v_mul_f32_e32 v0, v0, v1
	v_cvt_pk_bf16_f32 v0, v0, s0
	ds_write_b16 v138, v0 offset:15040
	v_mul_f32_e32 v0, v31, v31
	v_mul_f32_e32 v1, v47, v47
	v_fmac_f32_e32 v0, v15, v15
	v_fmac_f32_e32 v1, v63, v63
	v_add_f32_e32 v0, v0, v1
	ds_read_u16 v144, v138 offset:6912
	ds_read_u16 v145, v138 offset:6976
	ds_read_u16 v146, v138 offset:7040
	ds_read_u16 v147, v138 offset:7104
	s_nop 1
	v_add_f32_dpp v0, v0, v0 quad_perm:[1,0,3,2] row_mask:0xf bank_mask:0xf
	s_nop 1
	v_add_f32_dpp v0, v0, v0 quad_perm:[2,3,0,1] row_mask:0xf bank_mask:0xf
	s_nop 1
	v_add_f32_dpp v0, v0, v0 row_half_mirror row_mask:0xf bank_mask:0xf
	s_nop 1
	v_add_f32_dpp v0, v0, v0 row_mirror row_mask:0xf bank_mask:0xf
	s_waitcnt lgkmcnt(0)
	v_mov_b32_e32 v1, v0
	s_nop 1
	v_permlane16_swap_b32_e32 v0, v1
	v_add_f32_e32 v0, v0, v1
	v_fmamk_f32 v0, v0, 0x3c000000, v199
	v_rsq_f32_e32 v0, v0
	v_lshlrev_b32_e32 v1, 16, v144
	v_mul_f32_e32 v3, 0xbfb8aa3b, v1
	v_exp_f32_e32 v3, v3
	v_mul_f32_e32 v2, v15, v0
	v_mul_f32_e32 v2, v113, v2
	v_add_f32_e32 v3, 1.0, v3
	v_rcp_f32_e32 v3, v3
	s_nop 0
	v_mul_f32_e32 v1, v3, v1
	v_mul_f32_e32 v1, v2, v1
	v_cvt_pk_bf16_f32 v1, v1, s0
	ds_write_b16 v138, v1 offset:15104
	v_mul_f32_e32 v2, v31, v0
	v_mul_f32_e32 v2, v130, v2
	v_lshlrev_b32_e32 v1, 16, v145
	v_mul_f32_e32 v3, 0xbfb8aa3b, v1
	v_exp_f32_e32 v3, v3
	s_nop 0
	v_add_f32_e32 v3, 1.0, v3
	v_rcp_f32_e32 v3, v3
	s_nop 0
	v_mul_f32_e32 v1, v3, v1
	v_mul_f32_e32 v1, v2, v1
	v_cvt_pk_bf16_f32 v1, v1, s0
	ds_write_b16 v138, v1 offset:15168
	v_mul_f32_e32 v2, v63, v0
	v_mul_f32_e32 v2, v131, v2
	v_mul_f32_e32 v0, v47, v0
	v_mul_f32_e32 v0, v132, v0
	v_lshlrev_b32_e32 v1, 16, v146
	v_mul_f32_e32 v3, 0xbfb8aa3b, v1
	v_exp_f32_e32 v3, v3
	s_nop 0
	v_add_f32_e32 v3, 1.0, v3
	v_rcp_f32_e32 v3, v3
	s_nop 0
	v_mul_f32_e32 v1, v3, v1
	v_mul_f32_e32 v1, v2, v1
	v_cvt_pk_bf16_f32 v1, v1, s0
	ds_write_b16 v138, v1 offset:15232
	v_lshlrev_b32_e32 v1, 16, v147
	v_mul_f32_e32 v2, 0xbfb8aa3b, v1
	v_exp_f32_e32 v2, v2
	s_nop 0
	v_add_f32_e32 v2, 1.0, v2
	v_rcp_f32_e32 v2, v2
	s_nop 0
	v_mul_f32_e32 v1, v2, v1
	v_mul_f32_e32 v0, v0, v1
	v_cvt_pk_bf16_f32 v0, v0, s0
	ds_write_b16 v138, v0 offset:15296
	v_lshlrev_b64 v[0:1], 11, v[122:123]
	v_lshl_add_u64 v[0:1], s[54:55], 0, v[0:1]
	v_lshl_add_u64 v[0:1], v[0:1], 0, v[160:161]
	v_lshl_add_u64 v[4:5], v[0:1], 0, v[120:121]
	ds_read_b128 v[0:3], v140 offset:8192
	v_add_co_u32_e32 v6, vcc, s2, v4
	s_movk_i32 s2, 0x6000
	s_nop 0
	v_addc_co_u32_e32 v7, vcc, 0, v5, vcc
	s_waitcnt lgkmcnt(0)
	global_store_dwordx4 v[4:5], v[0:3], off
	ds_read_b128 v[0:3], v140 offset:9216
	s_waitcnt lgkmcnt(0)
	global_store_dwordx4 v[6:7], v[0:3], off
	ds_read_b128 v[0:3], v140 offset:10240
	v_add_co_u32_e32 v6, vcc, s49, v4
	s_nop 1
	v_addc_co_u32_e32 v7, vcc, 0, v5, vcc
	s_waitcnt lgkmcnt(0)
	global_store_dwordx4 v[6:7], v[0:3], off
	ds_read_b128 v[0:3], v140 offset:11264
	v_add_co_u32_e32 v6, vcc, s2, v4
	s_mov_b32 s2, 0xa000
	s_nop 0
	v_addc_co_u32_e32 v7, vcc, 0, v5, vcc
	s_waitcnt lgkmcnt(0)
	global_store_dwordx4 v[6:7], v[0:3], off
	ds_read_b128 v[0:3], v140 offset:12288
	v_add_co_u32_e32 v6, vcc, s42, v4
	s_nop 1
	v_addc_co_u32_e32 v7, vcc, 0, v5, vcc
	s_waitcnt lgkmcnt(0)
	global_store_dwordx4 v[6:7], v[0:3], off
	ds_read_b128 v[0:3], v140 offset:13312
	v_add_co_u32_e32 v6, vcc, s2, v4
	s_movk_i32 s2, 0x7ff
	s_nop 0
	v_addc_co_u32_e32 v7, vcc, 0, v5, vcc
	s_waitcnt lgkmcnt(0)
	global_store_dwordx4 v[6:7], v[0:3], off
	ds_read_b128 v[0:3], v140 offset:14336
	v_add_co_u32_e32 v6, vcc, 0xc000, v4
	s_nop 1
	v_addc_co_u32_e32 v7, vcc, 0, v5, vcc
	s_waitcnt lgkmcnt(0)
	global_store_dwordx4 v[6:7], v[0:3], off
	ds_read_b128 v[0:3], v140 offset:15360
	v_add_co_u32_e32 v4, vcc, 0xe000, v4
	s_nop 1
	v_addc_co_u32_e32 v5, vcc, 0, v5, vcc
	s_waitcnt lgkmcnt(0)
	global_store_dwordx4 v[4:5], v[0:3], off
	v_cmp_lt_i32_e32 vcc, s2, v111
	s_or_b64 s[40:41], vcc, s[40:41]
	v_add_u32_e32 v0, 0x800, v111
	v_mov_b32_e32 v111, v0
	s_andn2_b64 exec, exec, s[40:41]
	s_cbranch_execz .LBB0_880
